# static-priority strategy: all per-cluster s_setprio flips removed (nine GEMM K loops + mLSTM chunk loop); waves arbitrate by age only
# speedup vs baseline: 1.0111x; 1.0024x over previous
.LBB0_371:
	s_cmp_gt_i32 s68, 0
	s_cselect_b64 s[70:71], -1, 0
	v_cndmask_b32_e64 v109, 0, 1, s[70:71]
	s_cmp_lt_i32 s68, 3
	v_readfirstlane_b32 s70, v109
	s_cselect_b32 s70, s70, 2
	s_cmp_lt_i32 s68, 6
	s_cselect_b32 s70, s70, 3
	s_add_i32 s71, s70, 1
	s_mul_i32 s71, s71, s70
	s_lshr_b32 s71, s71, 1
	s_mul_i32 vcc_lo, s71, 0xffffdf00
	s_add_i32 vcc_lo, vcc_lo, 0
	v_add_u32_e32 v109, vcc_lo, v108
	v_lshl_or_b32 v146, s70, 4, v161
	v_mad_u32_u24 v147, v146, s91, v104
	ds_read_b128 v[110:113], v109
	ds_read_b128 v[114:117], v109 offset:64
	ds_read_b128 v[118:121], v147
	ds_read_b128 v[122:125], v147 offset:64
	ds_read_b128 v[126:129], v109 offset:128
	ds_read_b128 v[130:133], v109 offset:192
	ds_read_b128 v[134:137], v147 offset:128
	ds_read_b128 v[138:141], v147 offset:192
	ds_read_b128 v[142:145], v109 offset:256
	ds_read_b128 v[166:169], v109 offset:320
	ds_read_b128 v[186:189], v147 offset:256
	ds_read_b128 v[190:193], v147 offset:320
	ds_read_b128 v[194:197], v109 offset:384
	ds_read_b128 v[198:201], v109 offset:448
	ds_read_b128 v[202:205], v147 offset:384
	ds_read_b128 v[206:209], v147 offset:448
	s_lshl_b32 s70, s71, 6
	v_lshl_add_u32 v109, v146, 2, 0
	s_sub_i32 s70, 0, s70
	v_add_u32_e32 v109, 0x20a00, v109
	v_add_u32_e32 v147, s70, v106
	v_add_u32_e32 v147, 0x20b00, v147
	ds_read_b32 v109, v109
	ds_read_b128 v[210:213], v147
	s_waitcnt lgkmcnt(14)
	v_mfma_f32_16x16x32_bf16 v[110:113], v[110:113], v[118:121], 0
	v_mfma_f32_16x16x32_bf16 v[110:113], v[114:117], v[122:125], v[110:113]
	s_waitcnt lgkmcnt(11)
	v_mfma_f32_16x16x32_bf16 v[110:113], v[126:129], v[134:137], v[110:113]
	s_waitcnt lgkmcnt(10)
	v_mfma_f32_16x16x32_bf16 v[110:113], v[130:133], v[138:141], v[110:113]
	s_waitcnt lgkmcnt(7)
	v_mfma_f32_16x16x32_bf16 v[110:113], v[142:145], v[186:189], v[110:113]
	s_waitcnt lgkmcnt(6)
	v_mfma_f32_16x16x32_bf16 v[110:113], v[166:169], v[190:193], v[110:113]
	s_waitcnt lgkmcnt(3)
	v_mfma_f32_16x16x32_bf16 v[110:113], v[194:197], v[202:205], v[110:113]
	s_waitcnt lgkmcnt(2)
	v_mfma_f32_16x16x32_bf16 v[110:113], v[198:201], v[206:209], v[110:113]
	s_waitcnt lgkmcnt(0)
	v_add_f32_e32 v115, v109, v210
	v_mul_f32_e32 v115, 0x3fb8aa3b, v115
	v_exp_f32_e32 v115, v115
	v_add_f32_e32 v116, v109, v212
	v_mul_f32_e32 v116, 0x3fb8aa3b, v116
	s_lshl_b32 s70, s71, 4
	v_mul_f32_e32 v110, v115, v110
	v_add_f32_e32 v115, v109, v211
	v_mul_f32_e32 v115, 0x3fb8aa3b, v115
	v_exp_f32_e32 v115, v115
	v_add_f32_e32 v109, v109, v213
	v_exp_f32_e32 v116, v116
	v_mul_f32_e32 v109, 0x3fb8aa3b, v109
	v_subrev_u32_e32 v114, s70, v107
	v_exp_f32_e32 v109, v109
	v_cmp_le_i32_e32 vcc, v114, v146
	v_mul_f32_e32 v111, v115, v111
	v_add_u32_e32 v115, 2, v114
	v_cndmask_b32_e32 v110, 0, v110, vcc
	v_cmp_lt_i32_e32 vcc, v114, v146
	v_mul_f32_e32 v112, v116, v112
	v_add_u32_e32 v114, 3, v114
	v_cndmask_b32_e32 v111, 0, v111, vcc
	v_cmp_le_i32_e32 vcc, v115, v146
	v_mul_f32_e32 v109, v109, v113
	v_cvt_pk_bf16_f32 v110, v110, v111
	s_lshl_b32 s70, s71, 5
	v_cndmask_b32_e32 v112, 0, v112, vcc
	v_cmp_le_i32_e32 vcc, v114, v146
	s_add_i32 s69, s69, -1
	s_add_i32 s68, s68, 1
	v_cndmask_b32_e32 v109, 0, v109, vcc
	v_cvt_pk_bf16_f32 v111, v112, v109
	v_mul_u32_u24_e32 v109, 0x90, v146
	v_subrev_u32_e32 v109, s70, v109
	v_add3_u32 v109, 0, v109, v105
	v_add_u32_e32 v105, 32, v105
	v_add_u32_e32 v106, 64, v106
	v_add_u32_e32 v107, 16, v107
	v_add_u32_e32 v108, 0x2100, v108
	s_cmp_eq_u32 s69, 0
	ds_write_b64 v109, v[110:111]
	s_cbranch_scc0 .LBB0_371
	s_branch .LBB0_374

.Lpf_skip3:
	s_waitcnt lgkmcnt(7)
	v_mfma_f32_16x16x32_bf16 v[104:107], v[104:107], v[116:119], 0
	s_mov_b32 s68, 0
	s_waitcnt lgkmcnt(6)
	v_mfma_f32_16x16x32_bf16 v[104:107], v[108:111], v[120:123], v[104:107]
	s_waitcnt lgkmcnt(5)
	v_mfma_f32_16x16x32_bf16 v[104:107], v[112:115], v[124:127], v[104:107]
	s_waitcnt lgkmcnt(4)
	v_mfma_f32_16x16x32_bf16 v[104:107], v[186:189], v[128:131], v[104:107]
	s_waitcnt lgkmcnt(3)
	v_mfma_f32_16x16x32_bf16 v[104:107], v[190:193], v[132:135], v[104:107]
	s_waitcnt lgkmcnt(2)
	v_mfma_f32_16x16x32_bf16 v[104:107], v[194:197], v[136:139], v[104:107]
	s_waitcnt lgkmcnt(1)
	v_mfma_f32_16x16x32_bf16 v[104:107], v[198:201], v[140:143], v[104:107]
	s_waitcnt lgkmcnt(0)
	v_mfma_f32_16x16x32_bf16 v[112:115], v[202:205], v[144:147], v[104:107]
	s_nop 4
	ds_read_b128 v[104:107], v168 offset:16896
	ds_read_b128 v[108:111], v168 offset:16960
	ds_read_b128 v[186:189], v168 offset:17024
	ds_read_b128 v[190:193], v168 offset:17088
	ds_read_b128 v[194:197], v168 offset:17152
	ds_read_b128 v[198:201], v168 offset:17216
	ds_read_b128 v[202:205], v168 offset:17280
	ds_read_b128 v[206:209], v168 offset:17344
	s_cmp_eq_u32 s1, 31
	s_cbranch_scc1 .Lpf_skip4
	global_load_dwordx4 v[16:19], v215, s[18:19]
	global_load_dwordx4 v[84:87], v215, s[18:19] offset:2048
.Lpf_skip4:
	s_waitcnt lgkmcnt(7)
	v_mfma_f32_16x16x32_bf16 v[104:107], v[104:107], v[116:119], 0
	s_waitcnt lgkmcnt(6)
	v_mfma_f32_16x16x32_bf16 v[104:107], v[108:111], v[120:123], v[104:107]
	s_waitcnt lgkmcnt(5)
	v_mfma_f32_16x16x32_bf16 v[104:107], v[186:189], v[124:127], v[104:107]
	s_waitcnt lgkmcnt(4)
	v_mfma_f32_16x16x32_bf16 v[104:107], v[190:193], v[128:131], v[104:107]
	s_waitcnt lgkmcnt(3)
	v_mfma_f32_16x16x32_bf16 v[104:107], v[194:197], v[132:135], v[104:107]
	s_waitcnt lgkmcnt(2)
	v_mfma_f32_16x16x32_bf16 v[104:107], v[198:201], v[136:139], v[104:107]
	s_waitcnt lgkmcnt(1)
	v_mfma_f32_16x16x32_bf16 v[104:107], v[202:205], v[140:143], v[104:107]
	s_waitcnt lgkmcnt(0)
	v_mfma_f32_16x16x32_bf16 v[108:111], v[206:209], v[144:147], v[104:107]
	s_nop 4
	v_mov_b32_e32 v104, 0
	s_and_b64 vcc, exec, s[10:11]
	v_mov_b32_e32 v105, 0
	v_mov_b32_e32 v106, 0
	v_mov_b32_e32 v107, 0
	s_cbranch_vccz .LBB0_376
	ds_read_b128 v[104:107], v168 offset:33792
	ds_read_b128 v[186:189], v168 offset:33856
	ds_read_b128 v[190:193], v168 offset:33920
	ds_read_b128 v[194:197], v168 offset:33984
	ds_read_b128 v[198:201], v168 offset:34048
	ds_read_b128 v[202:205], v168 offset:34112
	ds_read_b128 v[206:209], v168 offset:34176
	ds_read_b128 v[210:213], v168 offset:34240
	s_waitcnt lgkmcnt(7)
	v_mfma_f32_16x16x32_bf16 v[104:107], v[104:107], v[116:119], 0
	s_waitcnt lgkmcnt(6)
	v_mfma_f32_16x16x32_bf16 v[104:107], v[186:189], v[120:123], v[104:107]
	s_waitcnt lgkmcnt(5)
	v_mfma_f32_16x16x32_bf16 v[104:107], v[190:193], v[124:127], v[104:107]
	s_waitcnt lgkmcnt(4)
	v_mfma_f32_16x16x32_bf16 v[104:107], v[194:197], v[128:131], v[104:107]
	s_waitcnt lgkmcnt(3)
	v_mfma_f32_16x16x32_bf16 v[104:107], v[198:201], v[132:135], v[104:107]
	s_waitcnt lgkmcnt(2)
	v_mfma_f32_16x16x32_bf16 v[104:107], v[202:205], v[136:139], v[104:107]
	s_waitcnt lgkmcnt(1)
	v_mfma_f32_16x16x32_bf16 v[104:107], v[206:209], v[140:143], v[104:107]
	s_waitcnt lgkmcnt(0)
	v_mfma_f32_16x16x32_bf16 v[104:107], v[210:213], v[144:147], v[104:107]
	s_mov_b32 s68, 4

.LBB0_395:
	v_or_b32_e32 v89, s4, v161
	v_mul_lo_u32 v89, v89, s85
	s_waitcnt lgkmcnt(1)
	v_add_lshl_u32 v101, v157, s97, 3
	v_add_u32_e32 v100, 0, v89
	v_and_b32_e32 v89, 56, v101
	v_add_u32_e32 v93, 8, v101
	v_bitop3_b32 v102, v101, 32, 56 bitop3:0x6c
	v_add_u32_e32 v101, 40, v101
	v_mul_u32_u24_e32 v92, 0x90, v161
	v_and_b32_e32 v93, 56, v93
	v_and_b32_e32 v101, 56, v101
	s_waitcnt lgkmcnt(0)
	s_barrier
	v_mov_b32_e32 v88, s89
	v_lshl_add_u32 v89, v89, 1, v100
	v_lshl_add_u32 v93, v93, 1, v100
	v_add3_u32 v140, s86, v162, v92
	v_lshl_add_u32 v136, v102, 1, v100
	v_lshl_add_u32 v100, v101, 1, v100
	ds_read_b32 v144, v88
	ds_read_b128 v[88:91], v89 offset:33792
	ds_read_b128 v[92:95], v93 offset:36096
	s_waitcnt lgkmcnt(3)
	ds_read_b128 v[96:99], v140
	ds_read_b128 v[100:103], v100 offset:36096
	ds_read_b128 v[104:107], v140 offset:2304
	ds_read_b128 v[108:111], v140 offset:64
	ds_read_b128 v[112:115], v140 offset:4608
	ds_read_b128 v[116:119], v140 offset:2368
	ds_read_b128 v[120:123], v140 offset:6912
	ds_read_b128 v[124:127], v140 offset:4672
	ds_read_b128 v[128:131], v140 offset:9216
	ds_read_b128 v[132:135], v140 offset:6976
	ds_read_b128 v[136:139], v136 offset:33792
	ds_read_b128 v[140:143], v140 offset:9280
	s_waitcnt lgkmcnt(14)
	v_pk_mul_f32 v[70:71], v[70:71], v[144:145] op_sel_hi:[1,0]
	v_pk_mul_f32 v[68:69], v[68:69], v[144:145] op_sel_hi:[1,0]
	v_pk_mul_f32 v[66:67], v[66:67], v[144:145] op_sel_hi:[1,0]
	v_pk_mul_f32 v[64:65], v[64:65], v[144:145] op_sel_hi:[1,0]
	v_pk_mul_f32 v[62:63], v[62:63], v[144:145] op_sel_hi:[1,0]
	v_pk_mul_f32 v[60:61], v[60:61], v[144:145] op_sel_hi:[1,0]
	v_pk_mul_f32 v[58:59], v[58:59], v[144:145] op_sel_hi:[1,0]
	v_pk_mul_f32 v[56:57], v[56:57], v[144:145] op_sel_hi:[1,0]
	v_pk_mul_f32 v[54:55], v[54:55], v[144:145] op_sel_hi:[1,0]
	v_pk_mul_f32 v[52:53], v[52:53], v[144:145] op_sel_hi:[1,0]
	v_pk_mul_f32 v[50:51], v[50:51], v[144:145] op_sel_hi:[1,0]
	v_pk_mul_f32 v[48:49], v[48:49], v[144:145] op_sel_hi:[1,0]
	v_pk_mul_f32 v[46:47], v[46:47], v[144:145] op_sel_hi:[1,0]
	v_pk_mul_f32 v[44:45], v[44:45], v[144:145] op_sel_hi:[1,0]
	v_pk_mul_f32 v[42:43], v[42:43], v[144:145] op_sel_hi:[1,0]
	v_pk_mul_f32 v[40:41], v[40:41], v[144:145] op_sel_hi:[1,0]
	v_pk_mul_f32 v[38:39], v[38:39], v[144:145] op_sel_hi:[1,0]
	v_pk_mul_f32 v[36:37], v[36:37], v[144:145] op_sel_hi:[1,0]
	v_pk_mul_f32 v[34:35], v[34:35], v[144:145] op_sel_hi:[1,0]
	v_pk_mul_f32 v[32:33], v[32:33], v[144:145] op_sel_hi:[1,0]
	s_waitcnt lgkmcnt(11)
	v_mfma_f32_16x16x32_bf16 v[68:71], v[88:91], v[96:99], v[68:71]
	v_mfma_f32_16x16x32_bf16 v[64:67], v[92:95], v[96:99], v[64:67]
	s_waitcnt lgkmcnt(9)
	v_mfma_f32_16x16x32_bf16 v[60:63], v[88:91], v[104:107], v[60:63]
	v_mfma_f32_16x16x32_bf16 v[56:59], v[92:95], v[104:107], v[56:59]
	s_waitcnt lgkmcnt(7)
	v_mfma_f32_16x16x32_bf16 v[52:55], v[88:91], v[112:115], v[52:55]
	v_mfma_f32_16x16x32_bf16 v[48:51], v[92:95], v[112:115], v[48:51]
	s_waitcnt lgkmcnt(5)
	v_mfma_f32_16x16x32_bf16 v[44:47], v[88:91], v[120:123], v[44:47]
	v_mfma_f32_16x16x32_bf16 v[40:43], v[92:95], v[120:123], v[40:43]
	s_waitcnt lgkmcnt(3)
	v_mfma_f32_16x16x32_bf16 v[36:39], v[88:91], v[128:131], v[36:39]
	v_mfma_f32_16x16x32_bf16 v[32:35], v[92:95], v[128:131], v[32:35]
	s_waitcnt lgkmcnt(1)
	v_mfma_f32_16x16x32_bf16 v[68:71], v[136:139], v[108:111], v[68:71]
	v_mfma_f32_16x16x32_bf16 v[64:67], v[100:103], v[108:111], v[64:67]
	v_mfma_f32_16x16x32_bf16 v[60:63], v[136:139], v[116:119], v[60:63]
	v_mfma_f32_16x16x32_bf16 v[56:59], v[100:103], v[116:119], v[56:59]
	v_mfma_f32_16x16x32_bf16 v[52:55], v[136:139], v[124:127], v[52:55]
	v_mfma_f32_16x16x32_bf16 v[48:51], v[100:103], v[124:127], v[48:51]
	v_mfma_f32_16x16x32_bf16 v[44:47], v[136:139], v[132:135], v[44:47]
	v_mfma_f32_16x16x32_bf16 v[40:43], v[100:103], v[132:135], v[40:43]
	s_waitcnt lgkmcnt(0)
	v_mfma_f32_16x16x32_bf16 v[36:39], v[136:139], v[140:143], v[36:39]
	v_mfma_f32_16x16x32_bf16 v[32:35], v[100:103], v[140:143], v[32:35]
	s_and_b64 vcc, exec, s[66:67]
	s_cbranch_vccz .LBB0_397
	v_add3_u32 v90, s22, v158, v155
	v_cvt_pk_bf16_f32 v88, v68, v69
	v_cvt_pk_bf16_f32 v89, v70, v71
	ds_write_b64 v90, v[88:89]
	v_cvt_pk_bf16_f32 v88, v64, v65
	v_cvt_pk_bf16_f32 v89, v66, v67
	ds_write_b64 v90, v[88:89] offset:32
	v_cvt_pk_bf16_f32 v88, v60, v61
	v_cvt_pk_bf16_f32 v89, v62, v63
	ds_write_b64 v90, v[88:89] offset:8448
	v_cvt_pk_bf16_f32 v88, v56, v57
	v_cvt_pk_bf16_f32 v89, v58, v59
	ds_write_b64 v90, v[88:89] offset:8480
	v_cvt_pk_bf16_f32 v88, v52, v53
	v_cvt_pk_bf16_f32 v89, v54, v55
	ds_write_b64 v90, v[88:89] offset:16896
	v_cvt_pk_bf16_f32 v88, v48, v49
	v_cvt_pk_bf16_f32 v89, v50, v51
	ds_write_b64 v90, v[88:89] offset:16928
	v_cvt_pk_bf16_f32 v88, v44, v45
	v_cvt_pk_bf16_f32 v89, v46, v47
	ds_write_b64 v90, v[88:89] offset:25344
	v_cvt_pk_bf16_f32 v88, v40, v41
	v_cvt_pk_bf16_f32 v89, v42, v43
	ds_write_b64 v90, v[88:89] offset:25376
	v_cvt_pk_bf16_f32 v88, v36, v37
	v_cvt_pk_bf16_f32 v89, v38, v39
	ds_write_b64 v90, v[88:89] offset:33792
	v_cvt_pk_bf16_f32 v88, v32, v33
	v_cvt_pk_bf16_f32 v89, v34, v35
	ds_write_b64 v90, v[88:89] offset:33824
